# prep: weight-tile job lookup resumes from the previous tile's job (tile ids are monotonic per workgroup) instead of rescanning all 20 jobs before each tile's loads
# speedup vs baseline: 1.0093x; 1.0093x over previous
.LBB0_851:
	s_and_b64 vcc, exec, s[10:11]
	s_cbranch_vccnz .LBB0_905
	v_lshlrev_b32_e32 v1, 2, v30
	v_lshlrev_b32_e32 v18, 3, v30
	v_add_u32_e32 v19, 0x200, v30
	v_add_u32_e32 v23, 0x400, v30
	v_add_u32_e32 v28, 0x600, v30
	v_and_b32_e32 v24, 60, v1
	v_and_b32_e32 v18, 0x78, v18
	v_ashrrev_i32_e32 v25, 4, v19
	v_ashrrev_i32_e32 v26, 4, v30
	s_movk_i32 s2, 0x104
	v_ashrrev_i32_e32 v27, 4, v23
	v_ashrrev_i32_e32 v28, 4, v28
	v_lshl_add_u32 v1, v24, 2, 0
	v_lshl_add_u32 v19, v25, 2, 0
	v_mul_u32_u24_e32 v20, 0x104, v18
	v_mul_lo_u32 v21, v26, s2
	v_mul_lo_u32 v22, v25, s2
	v_mul_lo_u32 v23, v27, s2
	v_mul_lo_u32 v32, v28, s2
	v_lshl_add_u32 v33, v26, 2, 0
	v_add_u32_e32 v29, v1, v21
	v_add_u32_e32 v30, v1, v22
	v_add_u32_e32 v31, v1, v23
	v_add_u32_e32 v32, v1, v32
	v_lshlrev_b32_e32 v18, 1, v18
	v_add_u32_e32 v33, v33, v20
	v_add_u32_e32 v34, v19, v20
	v_readlane_b32 s27, v252, 0
	s_mov_b32 s31, s26
	s_mov_b64 s[20:21], s[16:17]
	s_mov_b32 s28, s4
	s_mov_b32 s30, s19
	s_mov_b32 s29, s5
	s_mov_b32 s10, 0
	s_nop 0
	v_writelane_b32 v255, s10, 46
	v_writelane_b32 v255, s10, 47
	s_branch .LBB0_854

.LBB0_854:
	s_load_dwordx2 s[10:11], s[0:1], 0xb4
	s_mov_b32 s34, s18
	s_waitcnt vmcnt(0)
	v_pk_mul_f32 v[2:3], v[2:3], v[100:101] op_sel_hi:[1,0]
	v_pk_mul_f32 v[4:5], v[4:5], v[100:101] op_sel_hi:[1,0]
	v_pk_mul_f32 v[6:7], v[6:7], v[102:103] op_sel_hi:[1,0]
	v_pk_mul_f32 v[8:9], v[8:9], v[102:103] op_sel_hi:[1,0]
	v_pk_mul_f32 v[10:11], v[10:11], v[104:105] op_sel_hi:[1,0]
	v_pk_mul_f32 v[12:13], v[12:13], v[104:105] op_sel_hi:[1,0]
	v_pk_mul_f32 v[14:15], v[14:15], v[106:107] op_sel_hi:[1,0]
	v_pk_mul_f32 v[16:17], v[16:17], v[106:107] op_sel_hi:[1,0]
	ds_write2_b32 v29, v2, v3 offset1:1
	s_waitcnt lgkmcnt(0)
	ds_write2_b32 v29, v4, v5 offset0:2 offset1:3
	s_waitcnt lgkmcnt(0)
	ds_write2_b32 v30, v6, v7 offset1:1
	ds_write2_b32 v30, v8, v9 offset0:2 offset1:3
	ds_write2_b32 v31, v10, v11 offset1:1
	ds_write2_b32 v31, v12, v13 offset0:2 offset1:3
	ds_write2_b32 v32, v14, v15 offset1:1
	ds_write2_b32 v32, v16, v17 offset0:2 offset1:3
	s_waitcnt lgkmcnt(0)
	s_barrier
	s_add_i32 s27, s27, s11
	s_cmpk_gt_i32 s27, 0x51a3
	s_cselect_b64 s[14:15], -1, 0
	s_and_b64 vcc, exec, s[14:15]
	s_cbranch_vccnz .LBB0_853
	v_readlane_b32 s34, v255, 46
	v_readlane_b32 s36, v255, 47
	s_nop 0
	s_mov_b32 s25, s34
	s_lshl_b32 s31, s34, 7
	s_sub_i32 s36, s27, s36
	s_branch .LBB0_857

.LBB0_886:
	s_sub_i32 s10, s27, s24
	v_writelane_b32 v255, s34, 46
	v_writelane_b32 v255, s10, 47
	v_cvt_f32_u32_e32 v1, s37
	s_sub_i32 s25, 0, s37
	s_abs_i32 s11, s24
	s_ashr_i32 s10, s24, 31
	v_rcp_iflag_f32_e32 v1, v1
	s_nop 0
	v_mul_f32_e32 v1, 0x4f7ffffe, v1
	v_cvt_u32_f32_e32 v1, v1
	s_nop 0
	v_readfirstlane_b32 s31, v1
	s_mul_i32 s25, s25, s31
	s_mul_hi_u32 s25, s31, s25
	s_add_i32 s31, s31, s25
	s_mul_hi_u32 s25, s11, s31
	s_mul_i32 s31, s25, s37
	s_sub_i32 s11, s11, s31
	s_add_i32 s34, s25, 1
	s_sub_i32 s31, s11, s37
	s_cmp_ge_u32 s11, s37
	s_cselect_b32 s25, s34, s25
	s_cselect_b32 s11, s31, s11
	s_add_i32 s31, s25, 1
	s_cmp_ge_u32 s11, s37
	s_cselect_b32 s11, s31, s25
	s_xor_b32 s11, s11, s10
	s_sub_i32 s10, s11, s10
	s_mul_i32 s11, s10, s37
	s_lshl_b32 s31, s10, 6
	s_sub_i32 s10, s24, s11
	v_or_b32_e32 v2, s31, v24
	s_lshl_b32 s34, s10, 7
	v_ashrrev_i32_e32 v3, 31, v2
	v_mov_b32_e32 v1, v0
	v_add_u32_e32 v6, s34, v26
	v_cmp_gt_i32_e64 s[10:11], s35, v2
	v_lshl_add_u64 v[20:21], v[2:3], 2, s[12:13]
	v_ashrrev_i32_e32 v7, 31, v6
	v_mov_b64_e32 v[4:5], v[0:1]
	v_mov_b64_e32 v[2:3], v[0:1]
	s_and_saveexec_b64 s[12:13], s[10:11]
	s_cbranch_execz .LBB0_888
	v_mad_u64_u32 v[2:3], s[24:25], v6, s35, 0
	v_mov_b32_e32 v4, v3
	v_mad_u64_u32 v[4:5], s[24:25], v7, s35, v[4:5]
	v_mov_b32_e32 v3, v4
	v_lshl_add_u64 v[2:3], v[2:3], 2, v[20:21]
	global_load_dwordx4 v[2:5], v[2:3], off
